# Epi3 polls without s_sleep and slot stores as global (not flat) stores
# speedup vs baseline: 1.0067x; 1.0067x over previous
.LBB0_647:
	s_or_b64 exec, exec, s[0:1]
	v_lshlrev_b32_e32 v2, 4, v3
	v_add3_u32 v0, s57, v0, v2
	s_waitcnt lgkmcnt(0)
	s_movk_i32 s0, 0x100
	v_cmp_gt_i32_e64 s[4:5], s0, v0
	s_movk_i32 s0, 0xff
	v_cmp_lt_i32_e32 vcc, s0, v0
	s_waitcnt vmcnt(0) lgkmcnt(0)
	s_barrier
	s_and_saveexec_b64 s[0:1], vcc
	s_xor_b64 s[0:1], exec, s[0:1]
	s_lshl_b32 s2, s82, 8
	s_or_saveexec_b64 s[0:1], s[0:1]
	v_mov_b32_e32 v2, s2
	s_xor_b64 exec, exec, s[0:1]
	s_cbranch_execz .LBB0_651
	v_lshl_add_u32 v2, v0, 4, 0
	v_add_u32_e32 v2, 0x21c00, v2
	ds_read_b128 v[132:135], v2
	s_lshl_b32 s2, s82, 8
	s_ashr_i32 s81, s80, 31
	v_mov_b32_e32 v2, s2
	s_waitcnt lgkmcnt(0)
	v_mov_b32_e32 v137, v134
	v_add_u32_e32 v134, s2, v0
	v_mov_b32_e32 v136, v133
	v_mov_b32_e32 v133, v135
	v_ashrrev_i32_e32 v135, 31, v134
	v_pk_add_f32 v[132:133], v[136:137], v[132:133]
	v_lshl_add_u64 v[134:135], v[134:135], 4, s[36:37]
	v_pk_add_f32 v[132:133], v[132:133], v[132:133] op_sel:[0,1] op_sel_hi:[1,0]
	v_lshl_add_u64 v[134:135], s[80:81], 2, v[134:135]
	global_store_dword v[134:135], v132, off sc1

.Lx1_spin:
	global_load_dword v158, v[156:157], off sc1
	global_load_dword v204, v[156:157], off offset:4 sc1
	global_load_dword v159, v[156:157], off offset:8 sc1
	global_load_dword v205, v[156:157], off offset:12 sc1
	s_waitcnt vmcnt(0)
	v_cmp_u_f32_e32 vcc, v158, v204
	v_cmp_u_f32_e64 s[38:39], v159, v205
	s_or_b64 vcc, vcc, s[38:39]
	s_add_i32 s81, s81, -1
	s_cmp_eq_u32 s81, 0
	s_cbranch_scc1 .Lx1_done
	s_and_b64 exec, exec, vcc
	s_cbranch_execz .Lx1_done
	s_nop 0
	s_branch .Lx1_spin

.LBB0_768:
	s_or_b64 exec, exec, s[0:1]
	s_waitcnt lgkmcnt(0)
	s_waitcnt lgkmcnt(0)
	s_barrier
	s_and_saveexec_b64 s[0:1], s[4:5]
	s_cbranch_execz .LBB0_770
	v_lshl_add_u32 v132, v0, 4, 0
	v_add_u32_e32 v132, 0x21c00, v132
	ds_read_b128 v[132:135], v132
	s_ashr_i32 s81, s80, 31
	s_waitcnt lgkmcnt(0)
	v_mov_b32_e32 v136, v133
	v_mov_b32_e32 v137, v134
	v_mov_b32_e32 v133, v135
	v_pk_add_f32 v[132:133], v[136:137], v[132:133]
	v_lshl_add_u64 v[134:135], v[192:193], 4, s[62:63]
	v_pk_add_f32 v[132:133], v[132:133], v[132:133] op_sel:[0,1] op_sel_hi:[1,0]
	v_lshl_add_u64 v[134:135], s[80:81], 2, v[134:135]
	global_store_dword v[134:135], v132, off sc1

.Lx2_spin:
	global_load_dword v152, v[148:149], off sc1
	global_load_dword v154, v[148:149], off offset:4 sc1
	global_load_dword v153, v[148:149], off offset:8 sc1
	global_load_dword v155, v[148:149], off offset:12 sc1
	s_waitcnt vmcnt(0)
	v_cmp_u_f32_e32 vcc, v152, v154
	v_cmp_u_f32_e64 s[38:39], v153, v155
	s_or_b64 vcc, vcc, s[38:39]
	s_add_i32 s81, s81, -1
	s_cmp_eq_u32 s81, 0
	s_cbranch_scc1 .Lx2_done
	s_and_b64 exec, exec, vcc
	s_cbranch_execz .Lx2_done
	s_nop 0
	s_branch .Lx2_spin
